# adaLN GEMV in phase 0: all 64 weight-row loads of an item issued before the k-loop (register sets rotated), instead of 8 dependent load-wait-FMA round trips
# speedup vs baseline: 1.0109x; 1.0029x over previous
; __device__ __forceinline__ void p0_adaln(const Params& P, float* lf) {
;     ...
;     for (int item = blockIdx.x; item < 768; item += gridDim.x) {
;         const int l = item / 192, j0 = (item % 192) * 32;
;         const int col = lane & 31, kh = lane >> 5;
;         const float* w = ada_w + (size_t)l * 1024 * 6144 + j0 + col;
;         float acc[17];
; #pragma unroll
;         for (int r = 0; r < 17; ++r) acc[r] = 0.f;
;         const int kb = wave * 128 + kh * 64;
;         for (int k0 = kb; k0 < kb + 64; k0 += 8) {
;             float wv[8];
; #pragma unroll
;             for (int e = 0; e < 8; ++e) wv[e] = w[(size_t)(k0 + e) * 6144];
.LBB0_27:
	s_mul_hi_i32 s4, s26, 0x2aaaaaab
	s_lshr_b32 s5, s4, 31
	s_ashr_i32 s27, s4, 5
	s_add_i32 s27, s27, s5
	s_mul_i32 s4, s27, 0xc0
	s_sub_i32 s4, s26, s4
	s_lshl_b32 s8, s4, 5
	s_ashr_i32 s9, s8, 31
	s_mul_i32 s13, s27, 0x1800000
	s_lshl_b64 s[4:5], s[8:9], 2
	s_mul_hi_i32 s12, s27, 0x1800000
	s_add_u32 s4, s13, s4
	s_addc_u32 s5, s12, s5
	v_lshl_add_u64 v[138:139], v[136:137], 0, s[4:5]
	s_mov_b64 s[12:13], 0
	v_mov_b32_e32 v174, v172
	v_mov_b32_e32 v175, v171
	v_mov_b32_e32 v146, 0
	v_mov_b32_e32 v147, v133
	v_mov_b32_e32 v140, 0
	v_mov_b32_e32 v141, v133
	v_mov_b32_e32 v142, 0
	v_mov_b32_e32 v143, v133
	v_mov_b32_e32 v144, 0
	v_mov_b32_e32 v145, v133
	v_mov_b32_e32 v148, 0
	v_mov_b32_e32 v149, v133
	v_mov_b32_e32 v150, 0
	v_mov_b32_e32 v151, v133
	v_mov_b32_e32 v152, 0
	v_mov_b32_e32 v153, v133
	v_mov_b32_e32 v154, 0
	v_mov_b32_e32 v155, v133
	v_mov_b32_e32 v176, 0
	s_mov_b32 s98, 0xfffd6000
	s_mov_b32 s99, -1
	v_lshl_add_u64 v[248:249], v[138:139], 0, s[98:99]
	global_load_dword v180, v[248:249], off
	s_mov_b64 s[98:99], 0x6000
	v_lshl_add_u64 v[242:243], v[248:249], 0, s[98:99]
	global_load_dword v181, v[242:243], off
	s_mov_b64 s[98:99], 0xc000
	v_lshl_add_u64 v[244:245], v[248:249], 0, s[98:99]
	global_load_dword v182, v[244:245], off
	s_mov_b64 s[98:99], 0x12000
	v_lshl_add_u64 v[246:247], v[248:249], 0, s[98:99]
	global_load_dword v183, v[246:247], off
	s_mov_b64 s[98:99], 0x18000
	v_lshl_add_u64 v[240:241], v[248:249], 0, s[98:99]
	global_load_dword v164, v[240:241], off
	s_mov_b64 s[98:99], 0x1e000
	v_lshl_add_u64 v[242:243], v[248:249], 0, s[98:99]
	global_load_dword v165, v[242:243], off
	s_mov_b64 s[98:99], 0x24000
	v_lshl_add_u64 v[244:245], v[248:249], 0, s[98:99]
	global_load_dword v166, v[244:245], off
	s_mov_b64 s[98:99], 0x2a000
	v_lshl_add_u64 v[246:247], v[248:249], 0, s[98:99]
	global_load_dword v132, v[246:247], off
	s_mov_b64 s[98:99], 0x30000
	v_lshl_add_u64 v[240:241], v[248:249], 0, s[98:99]
	global_load_dword v184, v[240:241], off
	s_mov_b64 s[98:99], 0x36000
	v_lshl_add_u64 v[242:243], v[248:249], 0, s[98:99]
	global_load_dword v185, v[242:243], off
	s_mov_b64 s[98:99], 0x3c000
	v_lshl_add_u64 v[244:245], v[248:249], 0, s[98:99]
	global_load_dword v186, v[244:245], off
	s_mov_b64 s[98:99], 0x42000
	v_lshl_add_u64 v[246:247], v[248:249], 0, s[98:99]
	global_load_dword v187, v[246:247], off
	s_mov_b64 s[98:99], 0x48000
	v_lshl_add_u64 v[240:241], v[248:249], 0, s[98:99]
	global_load_dword v188, v[240:241], off
	s_mov_b64 s[98:99], 0x4e000
	v_lshl_add_u64 v[242:243], v[248:249], 0, s[98:99]
	global_load_dword v189, v[242:243], off
	s_mov_b64 s[98:99], 0x54000
	v_lshl_add_u64 v[244:245], v[248:249], 0, s[98:99]
	global_load_dword v190, v[244:245], off
	s_mov_b64 s[98:99], 0x5a000
	v_lshl_add_u64 v[246:247], v[248:249], 0, s[98:99]
	global_load_dword v191, v[246:247], off
	s_mov_b64 s[98:99], 0x60000
	v_lshl_add_u64 v[240:241], v[248:249], 0, s[98:99]
	global_load_dword v192, v[240:241], off
	s_mov_b64 s[98:99], 0x66000
	v_lshl_add_u64 v[242:243], v[248:249], 0, s[98:99]
	global_load_dword v193, v[242:243], off
	s_mov_b64 s[98:99], 0x6c000
	v_lshl_add_u64 v[244:245], v[248:249], 0, s[98:99]
	global_load_dword v194, v[244:245], off
	s_mov_b64 s[98:99], 0x72000
	v_lshl_add_u64 v[246:247], v[248:249], 0, s[98:99]
	global_load_dword v195, v[246:247], off
	s_mov_b64 s[98:99], 0x78000
	v_lshl_add_u64 v[240:241], v[248:249], 0, s[98:99]
	global_load_dword v196, v[240:241], off
	s_mov_b64 s[98:99], 0x7e000
	v_lshl_add_u64 v[242:243], v[248:249], 0, s[98:99]
	global_load_dword v197, v[242:243], off
	s_mov_b64 s[98:99], 0x84000
	v_lshl_add_u64 v[244:245], v[248:249], 0, s[98:99]
	global_load_dword v198, v[244:245], off
	s_mov_b64 s[98:99], 0x8a000
	v_lshl_add_u64 v[246:247], v[248:249], 0, s[98:99]
	global_load_dword v199, v[246:247], off
	s_mov_b64 s[98:99], 0x90000
	v_lshl_add_u64 v[240:241], v[248:249], 0, s[98:99]
	global_load_dword v200, v[240:241], off
	s_mov_b64 s[98:99], 0x96000
	v_lshl_add_u64 v[242:243], v[248:249], 0, s[98:99]
	global_load_dword v201, v[242:243], off
	s_mov_b64 s[98:99], 0x9c000
	v_lshl_add_u64 v[244:245], v[248:249], 0, s[98:99]
	global_load_dword v202, v[244:245], off
	s_mov_b64 s[98:99], 0xa2000
	v_lshl_add_u64 v[246:247], v[248:249], 0, s[98:99]
	global_load_dword v203, v[246:247], off
	s_mov_b64 s[98:99], 0xa8000
	v_lshl_add_u64 v[240:241], v[248:249], 0, s[98:99]
	global_load_dword v204, v[240:241], off
	s_mov_b64 s[98:99], 0xae000
	v_lshl_add_u64 v[242:243], v[248:249], 0, s[98:99]
	global_load_dword v205, v[242:243], off
	s_mov_b64 s[98:99], 0xb4000
	v_lshl_add_u64 v[244:245], v[248:249], 0, s[98:99]
	global_load_dword v206, v[244:245], off
	s_mov_b64 s[98:99], 0xba000
	v_lshl_add_u64 v[246:247], v[248:249], 0, s[98:99]
	global_load_dword v207, v[246:247], off
	s_mov_b64 s[98:99], 0xc0000
	v_lshl_add_u64 v[240:241], v[248:249], 0, s[98:99]
	global_load_dword v208, v[240:241], off
	s_mov_b64 s[98:99], 0xc6000
	v_lshl_add_u64 v[242:243], v[248:249], 0, s[98:99]
	global_load_dword v209, v[242:243], off
	s_mov_b64 s[98:99], 0xcc000
	v_lshl_add_u64 v[244:245], v[248:249], 0, s[98:99]
	global_load_dword v210, v[244:245], off
	s_mov_b64 s[98:99], 0xd2000
	v_lshl_add_u64 v[246:247], v[248:249], 0, s[98:99]
	global_load_dword v211, v[246:247], off
	s_mov_b64 s[98:99], 0xd8000
	v_lshl_add_u64 v[240:241], v[248:249], 0, s[98:99]
	global_load_dword v212, v[240:241], off
	s_mov_b64 s[98:99], 0xde000
	v_lshl_add_u64 v[242:243], v[248:249], 0, s[98:99]
	global_load_dword v213, v[242:243], off
	s_mov_b64 s[98:99], 0xe4000
	v_lshl_add_u64 v[244:245], v[248:249], 0, s[98:99]
; __device__ __forceinline__ void p0_adaln(const Params& P, float* lf) {
;     ...
;         for (int k0 = kb; k0 < kb + 64; k0 += 8) {
;             float wv[8];
; #pragma unroll
;             for (int e = 0; e < 8; ++e) wv[e] = w[(size_t)(k0 + e) * 6144];
; #pragma unroll
;             for (int e = 0; e < 8; ++e)
; #pragma unroll
;                 for (int r = 0; r < 17; ++r) acc[r] += sc[r * 1024 + k0 + e] * wv[e];
	global_load_dword v214, v[244:245], off
	s_mov_b64 s[98:99], 0xea000
	v_lshl_add_u64 v[246:247], v[248:249], 0, s[98:99]
	global_load_dword v215, v[246:247], off
	s_mov_b64 s[98:99], 0xf0000
	v_lshl_add_u64 v[240:241], v[248:249], 0, s[98:99]
	global_load_dword v216, v[240:241], off
	s_mov_b64 s[98:99], 0xf6000
	v_lshl_add_u64 v[242:243], v[248:249], 0, s[98:99]
	global_load_dword v217, v[242:243], off
	s_mov_b64 s[98:99], 0xfc000
	v_lshl_add_u64 v[244:245], v[248:249], 0, s[98:99]
	global_load_dword v218, v[244:245], off
	s_mov_b64 s[98:99], 0x102000
	v_lshl_add_u64 v[246:247], v[248:249], 0, s[98:99]
	global_load_dword v219, v[246:247], off
	s_mov_b64 s[98:99], 0x108000
	v_lshl_add_u64 v[240:241], v[248:249], 0, s[98:99]
	global_load_dword v220, v[240:241], off
	s_mov_b64 s[98:99], 0x10e000
	v_lshl_add_u64 v[242:243], v[248:249], 0, s[98:99]
	global_load_dword v221, v[242:243], off
	s_mov_b64 s[98:99], 0x114000
	v_lshl_add_u64 v[244:245], v[248:249], 0, s[98:99]
	global_load_dword v222, v[244:245], off
	s_mov_b64 s[98:99], 0x11a000
	v_lshl_add_u64 v[246:247], v[248:249], 0, s[98:99]
	global_load_dword v223, v[246:247], off
	s_mov_b64 s[98:99], 0x120000
	v_lshl_add_u64 v[240:241], v[248:249], 0, s[98:99]
	global_load_dword v224, v[240:241], off
	s_mov_b64 s[98:99], 0x126000
	v_lshl_add_u64 v[242:243], v[248:249], 0, s[98:99]
	global_load_dword v225, v[242:243], off
	s_mov_b64 s[98:99], 0x12c000
	v_lshl_add_u64 v[244:245], v[248:249], 0, s[98:99]
	global_load_dword v226, v[244:245], off
	s_mov_b64 s[98:99], 0x132000
	v_lshl_add_u64 v[246:247], v[248:249], 0, s[98:99]
	global_load_dword v227, v[246:247], off
	s_mov_b64 s[98:99], 0x138000
	v_lshl_add_u64 v[240:241], v[248:249], 0, s[98:99]
	global_load_dword v228, v[240:241], off
	s_mov_b64 s[98:99], 0x13e000
	v_lshl_add_u64 v[242:243], v[248:249], 0, s[98:99]
	global_load_dword v229, v[242:243], off
	s_mov_b64 s[98:99], 0x144000
	v_lshl_add_u64 v[244:245], v[248:249], 0, s[98:99]
	global_load_dword v230, v[244:245], off
	s_mov_b64 s[98:99], 0x14a000
	v_lshl_add_u64 v[246:247], v[248:249], 0, s[98:99]
	global_load_dword v231, v[246:247], off
	s_mov_b64 s[98:99], 0x150000
	v_lshl_add_u64 v[240:241], v[248:249], 0, s[98:99]
	global_load_dword v232, v[240:241], off
	s_mov_b64 s[98:99], 0x156000
	v_lshl_add_u64 v[242:243], v[248:249], 0, s[98:99]
	global_load_dword v233, v[242:243], off
	s_mov_b64 s[98:99], 0x15c000
	v_lshl_add_u64 v[244:245], v[248:249], 0, s[98:99]
	global_load_dword v234, v[244:245], off
	s_mov_b64 s[98:99], 0x162000
	v_lshl_add_u64 v[246:247], v[248:249], 0, s[98:99]
	global_load_dword v235, v[246:247], off
	s_mov_b64 s[98:99], 0x168000
	v_lshl_add_u64 v[240:241], v[248:249], 0, s[98:99]
	global_load_dword v236, v[240:241], off
	s_mov_b64 s[98:99], 0x16e000
	v_lshl_add_u64 v[242:243], v[248:249], 0, s[98:99]
	global_load_dword v237, v[242:243], off
	s_mov_b64 s[98:99], 0x174000
	v_lshl_add_u64 v[244:245], v[248:249], 0, s[98:99]
	global_load_dword v238, v[244:245], off
	s_mov_b64 s[98:99], 0x17a000
	v_lshl_add_u64 v[246:247], v[248:249], 0, s[98:99]
	global_load_dword v239, v[246:247], off
.LBB0_28:
	ds_read_b128 v[22:25], v174
	ds_read_b128 v[18:21], v174 offset:16
	ds_read_b128 v[6:9], v174 offset:4096
	ds_read_b128 v[2:5], v174 offset:4112
	ds_read_b128 v[34:37], v174 offset:8192
	ds_read_b128 v[42:45], v174 offset:8208
	ds_read_b128 v[14:17], v174 offset:12288
	ds_read_b128 v[10:13], v174 offset:12304
	ds_read_b128 v[50:53], v174 offset:16384
	ds_read_b128 v[54:57], v174 offset:16400
	ds_read_b128 v[30:33], v174 offset:20480
	ds_read_b128 v[26:29], v174 offset:20496
	ds_read_b128 v[62:65], v174 offset:24576
	ds_read_b128 v[70:73], v174 offset:24592
	ds_read_b128 v[46:49], v174 offset:28672
	ds_read_b128 v[38:41], v174 offset:28688
	ds_read_b128 v[78:81], v174 offset:32768
	ds_read_b128 v[86:89], v174 offset:32784
	ds_read_b128 v[66:69], v174 offset:36864
	ds_read_b128 v[58:61], v174 offset:36880
	ds_read_b128 v[94:97], v174 offset:40960
	ds_read_b128 v[98:101], v174 offset:40976
	ds_read_b128 v[82:85], v174 offset:45056
	ds_read_b128 v[74:77], v174 offset:45072
	ds_read_b128 v[106:109], v174 offset:49152
	ds_read_b128 v[114:117], v174 offset:49168
	ds_read_b128 v[102:105], v174 offset:53248
	ds_read_b128 v[90:93], v174 offset:53264
	ds_read_b128 v[122:125], v174 offset:57344
	ds_read_b128 v[126:129], v174 offset:57360
	ds_read_b128 v[118:121], v174 offset:61440
	ds_read_b128 v[110:113], v174 offset:61456
	v_add_u32_e32 v177, 0x10000, v174
	v_add_u32_e32 v178, 0x10010, v174
	v_add_u32_e32 v175, 8, v175
	v_add_u32_e32 v174, 32, v174
	ds_read_b128 v[156:159], v177
	ds_read_b128 v[160:163], v178
	s_waitcnt lgkmcnt(14)
	v_mov_b32_e32 v168, v22
	v_mov_b32_e32 v169, v6
	v_mov_b32_e32 v6, v23
	v_mov_b32_e32 v22, v24
	v_mov_b32_e32 v23, v8
	v_mov_b32_e32 v8, v25
	v_mov_b32_e32 v24, v18
	v_mov_b32_e32 v25, v2
	v_mov_b32_e32 v2, v19
	v_mov_b32_e32 v18, v20
	v_mov_b32_e32 v19, v4
	v_mov_b32_e32 v4, v21
	v_mov_b32_e32 v20, v34
	v_mov_b32_e32 v21, v14
	v_mov_b32_e32 v14, v35
	v_mov_b32_e32 v34, v36
	v_mov_b32_e32 v35, v16
	v_mov_b32_e32 v16, v37
	v_mov_b32_e32 v36, v42
	v_mov_b32_e32 v37, v10
	v_mov_b32_e32 v10, v43
	v_mov_b32_e32 v42, v44
	v_mov_b32_e32 v43, v12
	v_mov_b32_e32 v12, v45
	v_mov_b32_e32 v44, v50
	v_mov_b32_e32 v45, v30
	v_mov_b32_e32 v30, v51
	v_mov_b32_e32 v50, v52
	v_mov_b32_e32 v51, v32
	v_mov_b32_e32 v32, v53
	v_mov_b32_e32 v52, v54
	v_mov_b32_e32 v53, v26
	v_mov_b32_e32 v26, v55
	v_mov_b32_e32 v54, v56
	v_mov_b32_e32 v55, v28
	v_mov_b32_e32 v28, v57
	v_mov_b32_e32 v56, v62
	v_mov_b32_e32 v57, v46
	v_mov_b32_e32 v46, v63
	v_mov_b32_e32 v62, v64
	v_mov_b32_e32 v63, v48
	v_mov_b32_e32 v48, v65
	v_mov_b32_e32 v64, v70
	v_mov_b32_e32 v65, v38
	v_mov_b32_e32 v38, v71
	v_mov_b32_e32 v70, v72
	v_mov_b32_e32 v71, v40
	v_mov_b32_e32 v40, v73
	v_mov_b32_e32 v72, v78
	v_mov_b32_e32 v73, v66
	v_mov_b32_e32 v66, v79
	v_mov_b32_e32 v78, v80
	v_mov_b32_e32 v79, v68
	v_mov_b32_e32 v68, v81
	v_mov_b32_e32 v80, v86
	v_mov_b32_e32 v81, v58
	v_mov_b32_e32 v58, v87
	v_mov_b32_e32 v86, v88
	v_mov_b32_e32 v87, v60
	v_mov_b32_e32 v60, v89
	s_waitcnt lgkmcnt(13)
; __device__ __forceinline__ void p0_adaln(const Params& P, float* lf) {
;     ...
; #pragma unroll
;             for (int e = 0; e < 8; ++e)
; #pragma unroll
;                 for (int r = 0; r < 17; ++r) acc[r] += sc[r * 1024 + k0 + e] * wv[e];
	v_mov_b32_e32 v88, v94
	s_waitcnt lgkmcnt(11)
	v_mov_b32_e32 v89, v82
	v_mov_b32_e32 v82, v95
	v_mov_b32_e32 v94, v96
	v_mov_b32_e32 v95, v84
	v_mov_b32_e32 v84, v97
	v_mov_b32_e32 v96, v98
	s_waitcnt lgkmcnt(10)
	v_mov_b32_e32 v97, v74
	v_mov_b32_e32 v74, v99
	v_mov_b32_e32 v98, v100
	v_mov_b32_e32 v99, v76
	v_mov_b32_e32 v76, v101
	s_waitcnt lgkmcnt(9)
	v_mov_b32_e32 v100, v106
	s_waitcnt lgkmcnt(7)
	v_mov_b32_e32 v101, v102
	v_mov_b32_e32 v102, v107
	v_mov_b32_e32 v106, v108
	v_mov_b32_e32 v107, v104
	v_mov_b32_e32 v104, v109
	v_mov_b32_e32 v108, v114
	s_waitcnt lgkmcnt(6)
	v_mov_b32_e32 v109, v90
	v_mov_b32_e32 v90, v115
	v_mov_b32_e32 v114, v116
	v_mov_b32_e32 v115, v92
	v_mov_b32_e32 v92, v117
	s_waitcnt lgkmcnt(5)
	v_mov_b32_e32 v116, v122
	s_waitcnt lgkmcnt(3)
	v_mov_b32_e32 v117, v118
	v_mov_b32_e32 v118, v123
	v_mov_b32_e32 v122, v124
	v_mov_b32_e32 v123, v120
	v_mov_b32_e32 v120, v125
	v_mov_b32_e32 v124, v126
	s_waitcnt lgkmcnt(2)
	v_mov_b32_e32 v125, v110
	v_mov_b32_e32 v110, v127
	v_mov_b32_e32 v126, v128
	v_mov_b32_e32 v127, v112
	v_mov_b32_e32 v112, v129
	s_waitcnt vmcnt(56) lgkmcnt(1)
	v_pk_mul_f32 v[128:129], v[180:181], v[156:157]
	v_pk_mul_f32 v[156:157], v[182:183], v[158:159]
	s_waitcnt lgkmcnt(0)
	v_pk_mul_f32 v[158:159], v[164:165], v[160:161]
	v_pk_fma_f32 v[146:147], v[180:181], v[168:169], v[146:147] op_sel_hi:[0,1,1]
	v_mov_b32_e32 v160, v181
	v_pk_fma_f32 v[20:21], v[180:181], v[20:21], v[140:141] op_sel_hi:[0,1,1]
	v_pk_fma_f32 v[44:45], v[180:181], v[44:45], v[142:143] op_sel_hi:[0,1,1]
	v_pk_fma_f32 v[56:57], v[180:181], v[56:57], v[144:145] op_sel_hi:[0,1,1]
	v_pk_fma_f32 v[72:73], v[180:181], v[72:73], v[148:149] op_sel_hi:[0,1,1]
	v_pk_fma_f32 v[88:89], v[180:181], v[88:89], v[150:151] op_sel_hi:[0,1,1]
	v_pk_fma_f32 v[100:101], v[180:181], v[100:101], v[152:153] op_sel_hi:[0,1,1]
	v_pk_fma_f32 v[116:117], v[180:181], v[116:117], v[154:155] op_sel_hi:[0,1,1]
	v_pk_fma_f32 v[6:7], v[160:161], v[6:7], v[146:147] op_sel_hi:[0,1,1]
	v_pk_fma_f32 v[14:15], v[160:161], v[14:15], v[20:21] op_sel_hi:[0,1,1]
	v_pk_fma_f32 v[20:21], v[160:161], v[30:31], v[44:45] op_sel_hi:[0,1,1]
	v_pk_fma_f32 v[30:31], v[160:161], v[46:47], v[56:57] op_sel_hi:[0,1,1]
	v_pk_fma_f32 v[44:45], v[160:161], v[66:67], v[72:73] op_sel_hi:[0,1,1]
	v_pk_fma_f32 v[46:47], v[160:161], v[82:83], v[88:89] op_sel_hi:[0,1,1]
	v_pk_fma_f32 v[56:57], v[160:161], v[102:103], v[100:101] op_sel_hi:[0,1,1]
	v_pk_fma_f32 v[66:67], v[160:161], v[118:119], v[116:117] op_sel_hi:[0,1,1]
	v_mov_b32_e32 v168, v183
	v_add_f32_e32 v128, v176, v128
	v_pk_fma_f32 v[6:7], v[182:183], v[22:23], v[6:7] op_sel_hi:[0,1,1]
	v_pk_fma_f32 v[14:15], v[182:183], v[34:35], v[14:15] op_sel_hi:[0,1,1]
	v_pk_fma_f32 v[20:21], v[182:183], v[50:51], v[20:21] op_sel_hi:[0,1,1]
	v_pk_fma_f32 v[22:23], v[182:183], v[62:63], v[30:31] op_sel_hi:[0,1,1]
	v_pk_fma_f32 v[30:31], v[182:183], v[78:79], v[44:45] op_sel_hi:[0,1,1]
	v_pk_fma_f32 v[34:35], v[182:183], v[94:95], v[46:47] op_sel_hi:[0,1,1]
	v_pk_fma_f32 v[44:45], v[182:183], v[106:107], v[56:57] op_sel_hi:[0,1,1]
	v_pk_fma_f32 v[46:47], v[182:183], v[122:123], v[66:67] op_sel_hi:[0,1,1]
	v_add_f32_e32 v72, v128, v129
	v_pk_fma_f32 v[6:7], v[168:169], v[8:9], v[6:7] op_sel_hi:[0,1,1]
	v_pk_fma_f32 v[8:9], v[168:169], v[16:17], v[14:15] op_sel_hi:[0,1,1]
	v_pk_fma_f32 v[14:15], v[168:169], v[32:33], v[20:21] op_sel_hi:[0,1,1]
	v_pk_fma_f32 v[16:17], v[168:169], v[48:49], v[22:23] op_sel_hi:[0,1,1]
	v_pk_fma_f32 v[20:21], v[168:169], v[68:69], v[30:31] op_sel_hi:[0,1,1]
	v_pk_fma_f32 v[22:23], v[168:169], v[84:85], v[34:35] op_sel_hi:[0,1,1]
	v_pk_fma_f32 v[30:31], v[168:169], v[104:105], v[44:45] op_sel_hi:[0,1,1]
	v_pk_fma_f32 v[32:33], v[168:169], v[120:121], v[46:47] op_sel_hi:[0,1,1]
	v_mov_b32_e32 v178, v165
	v_add_f32_e32 v50, v72, v156
	v_pk_fma_f32 v[6:7], v[164:165], v[24:25], v[6:7] op_sel_hi:[0,1,1]
	v_pk_fma_f32 v[8:9], v[164:165], v[36:37], v[8:9] op_sel_hi:[0,1,1]
	v_pk_fma_f32 v[14:15], v[164:165], v[52:53], v[14:15] op_sel_hi:[0,1,1]
	v_pk_fma_f32 v[16:17], v[164:165], v[64:65], v[16:17] op_sel_hi:[0,1,1]
	v_pk_fma_f32 v[20:21], v[164:165], v[80:81], v[20:21] op_sel_hi:[0,1,1]
	v_pk_fma_f32 v[22:23], v[164:165], v[96:97], v[22:23] op_sel_hi:[0,1,1]
	v_pk_fma_f32 v[24:25], v[164:165], v[108:109], v[30:31] op_sel_hi:[0,1,1]
	v_pk_fma_f32 v[30:31], v[164:165], v[124:125], v[32:33] op_sel_hi:[0,1,1]
	v_add_f32_e32 v34, v50, v157
	v_pk_fma_f32 v[2:3], v[178:179], v[2:3], v[6:7] op_sel_hi:[0,1,1]
	v_pk_fma_f32 v[6:7], v[178:179], v[10:11], v[8:9] op_sel_hi:[0,1,1]
	v_pk_fma_f32 v[8:9], v[178:179], v[26:27], v[14:15] op_sel_hi:[0,1,1]
	v_pk_fma_f32 v[10:11], v[178:179], v[38:39], v[16:17] op_sel_hi:[0,1,1]
	v_pk_fma_f32 v[14:15], v[178:179], v[58:59], v[20:21] op_sel_hi:[0,1,1]
	v_pk_fma_f32 v[16:17], v[178:179], v[74:75], v[22:23] op_sel_hi:[0,1,1]
	v_pk_fma_f32 v[20:21], v[178:179], v[90:91], v[24:25] op_sel_hi:[0,1,1]
	v_pk_fma_f32 v[22:23], v[178:179], v[110:111], v[30:31] op_sel_hi:[0,1,1]
	v_add_f32_e32 v32, v34, v158
	v_pk_fma_f32 v[2:3], v[166:167], v[18:19], v[2:3] op_sel_hi:[0,1,1]
	v_pk_fma_f32 v[6:7], v[166:167], v[42:43], v[6:7] op_sel_hi:[0,1,1]
	v_pk_fma_f32 v[8:9], v[166:167], v[54:55], v[8:9] op_sel_hi:[0,1,1]
	v_pk_fma_f32 v[10:11], v[166:167], v[70:71], v[10:11] op_sel_hi:[0,1,1]
	v_pk_fma_f32 v[14:15], v[166:167], v[86:87], v[14:15] op_sel_hi:[0,1,1]
	v_pk_fma_f32 v[16:17], v[166:167], v[98:99], v[16:17] op_sel_hi:[0,1,1]
	v_pk_fma_f32 v[18:19], v[166:167], v[114:115], v[20:21] op_sel_hi:[0,1,1]
	v_pk_fma_f32 v[20:21], v[166:167], v[126:127], v[22:23] op_sel_hi:[0,1,1]
	v_mov_b32_e32 v167, v132
	v_add_f32_e32 v24, v32, v159
	v_pk_fma_f32 v[146:147], v[132:133], v[4:5], v[2:3] op_sel_hi:[0,1,1]
	v_pk_mul_f32 v[2:3], v[166:167], v[162:163]
	v_cmp_ge_i32_e64 s[4:5], v175, v131
	v_add_f32_e32 v2, v24, v2
	v_lshl_add_u64 v[138:139], v[138:139], 0, s[6:7]
	s_or_b64 s[12:13], s[4:5], s[12:13]
	v_pk_fma_f32 v[140:141], v[132:133], v[12:13], v[6:7] op_sel_hi:[0,1,1]
	v_pk_fma_f32 v[142:143], v[132:133], v[28:29], v[8:9] op_sel_hi:[0,1,1]
	v_pk_fma_f32 v[144:145], v[132:133], v[40:41], v[10:11] op_sel_hi:[0,1,1]
	v_pk_fma_f32 v[148:149], v[132:133], v[60:61], v[14:15] op_sel_hi:[0,1,1]
	v_pk_fma_f32 v[150:151], v[132:133], v[76:77], v[16:17] op_sel_hi:[0,1,1]
	v_pk_fma_f32 v[152:153], v[132:133], v[92:93], v[18:19] op_sel_hi:[0,1,1]
	v_pk_fma_f32 v[154:155], v[132:133], v[112:113], v[20:21] op_sel_hi:[0,1,1]
	v_add_f32_e32 v176, v2, v3
	s_waitcnt vmcnt(0)
; __device__ __forceinline__ void p0_adaln(const Params& P, float* lf) {
;     ...
;         for (int k0 = kb; k0 < kb + 64; k0 += 8) {
;             float wv[8];
; #pragma unroll
;             for (int e = 0; e < 8; ++e) wv[e] = w[(size_t)(k0 + e) * 6144];
; #pragma unroll
;             for (int e = 0; e < 8; ++e)
; #pragma unroll
;                 for (int r = 0; r < 17; ++r) acc[r] += sc[r * 1024 + k0 + e] * wv[e];
;         }
; #pragma unroll
;         for (int r = 0; r < 17; ++r) red[(wave * 17 + r) * 64 + lane] = acc[r];
;         __syncthreads();
;         for (int i = tid; i < 17 * 32; i += 512) {
;             const int r = i >> 5, jj = i & 31; float s = 0.f;
; #pragma unroll
;             for (int w8 = 0; w8 < 8; ++w8) s += red[(w8 * 17 + r) * 64 + jj] + red[(w8 * 17 + r) * 64 + 32 + jj];
	v_mov_b32_e32 v180, v184
	v_mov_b32_e32 v181, v185
	v_mov_b32_e32 v182, v186
	v_mov_b32_e32 v183, v187
	v_mov_b32_e32 v164, v188
	v_mov_b32_e32 v165, v189
	v_mov_b32_e32 v166, v190
	v_mov_b32_e32 v132, v191
	v_mov_b32_e32 v184, v192
	v_mov_b32_e32 v185, v193
	v_mov_b32_e32 v186, v194
	v_mov_b32_e32 v187, v195
	v_mov_b32_e32 v188, v196
	v_mov_b32_e32 v189, v197
	v_mov_b32_e32 v190, v198
	v_mov_b32_e32 v191, v199
	v_mov_b32_e32 v192, v200
	v_mov_b32_e32 v193, v201
	v_mov_b32_e32 v194, v202
	v_mov_b32_e32 v195, v203
	v_mov_b32_e32 v196, v204
	v_mov_b32_e32 v197, v205
	v_mov_b32_e32 v198, v206
	v_mov_b32_e32 v199, v207
	v_mov_b32_e32 v200, v208
	v_mov_b32_e32 v201, v209
	v_mov_b32_e32 v202, v210
	v_mov_b32_e32 v203, v211
	v_mov_b32_e32 v204, v212
	v_mov_b32_e32 v205, v213
	v_mov_b32_e32 v206, v214
	v_mov_b32_e32 v207, v215
	v_mov_b32_e32 v208, v216
	v_mov_b32_e32 v209, v217
	v_mov_b32_e32 v210, v218
	v_mov_b32_e32 v211, v219
	v_mov_b32_e32 v212, v220
	v_mov_b32_e32 v213, v221
	v_mov_b32_e32 v214, v222
	v_mov_b32_e32 v215, v223
	v_mov_b32_e32 v216, v224
	v_mov_b32_e32 v217, v225
	v_mov_b32_e32 v218, v226
	v_mov_b32_e32 v219, v227
	v_mov_b32_e32 v220, v228
	v_mov_b32_e32 v221, v229
	v_mov_b32_e32 v222, v230
	v_mov_b32_e32 v223, v231
	v_mov_b32_e32 v224, v232
	v_mov_b32_e32 v225, v233
	v_mov_b32_e32 v226, v234
	v_mov_b32_e32 v227, v235
	v_mov_b32_e32 v228, v236
	v_mov_b32_e32 v229, v237
	v_mov_b32_e32 v230, v238
	v_mov_b32_e32 v231, v239
	s_andn2_b64 exec, exec, s[12:13]
	s_cbranch_execnz .LBB0_28
	s_or_b64 exec, exec, s[12:13]
	ds_write2st64_b32 v173, v146, v147 offset1:1
	ds_write2st64_b32 v173, v140, v141 offset0:2 offset1:3
	ds_write2st64_b32 v173, v142, v143 offset0:4 offset1:5
	ds_write2st64_b32 v173, v144, v145 offset0:6 offset1:7
	ds_write2st64_b32 v173, v148, v149 offset0:8 offset1:9
	ds_write2st64_b32 v173, v150, v151 offset0:10 offset1:11
	ds_write2st64_b32 v173, v152, v153 offset0:12 offset1:13
	ds_write2st64_b32 v173, v154, v155 offset0:14 offset1:15
	ds_write_b32 v173, v176 offset:4096
	s_waitcnt lgkmcnt(0)
	s_barrier
	s_and_saveexec_b64 s[12:13], vcc
	s_cbranch_execz .LBB0_26
	s_mul_i32 s4, s27, 0x1800
	s_add_i32 s4, s4, s8
	v_or_b32_e32 v2, s4, v1
	v_ashrrev_i32_e32 v3, 31, v2
	s_mul_i32 s27, s27, 17
	v_lshl_add_u64 v[2:3], v[2:3], 2, s[18:19]
	v_lshl_add_u64 v[4:5], s[8:9], 2, v[134:135]
	s_mov_b64 s[8:9], 0
	v_mov_b32_e32 v6, v130
